# MLA fused block: cross-half row-max exchange by v_permlane32_swap instead of the ds_bpermute LDS round trip (lever 7: lane movement without LDS)
# baseline (speedup 1.0000x reference)
; template <int MODE>
; DI void attn_unit(LAS unsigned char* lds, const AttnArgs a) {
;     ...
;                 float mx = max3f(s0[0], s1[0], s0[1]);
;                 mx = max3f(mx, s1[1], s0[2]); mx = max3f(mx, s1[2], s0[3]); mx = max3f(mx, s1[3], s0[4]); mx = max3f(mx, s1[4], s0[5]);
;                 mx = max3f(mx, s1[5], s0[6]); mx = max3f(mx, s1[6], s0[7]); mx = max3f(mx, s1[7], s0[8]); mx = max3f(mx, s1[8], s0[9]);
;                 mx = max3f(mx, s1[9], s0[10]); mx = max3f(mx, s1[10], s0[11]); mx = max3f(mx, s1[11], s0[12]); mx = max3f(mx, s1[12], s0[13]);
;                 mx = max3f(mx, s1[13], s0[14]); mx = max3f(mx, s1[14], s0[15]); mx = fmaxf(mx, s1[15]);
;                 mx = fmaxf(mx, __shfl_xor(mx, 32));
;                 mnew = fmaxf(mrow, mx); alpha = ex2(mrow - mnew);
; #pragma unroll
;                 for (int i = 0; i < 16; ++i) {
;                     const float p0 = ex2(s0[i] - mnew), p1 = ex2(s1[i] - mnew);
;                     s0[i] = p0; s1[i] = p1; ls += p0 + p1;
;                 }
;             } else {
;                 float mx = -1e30f;
; #pragma unroll
;                 for (int i = 0; i < 16; ++i) {
;                     const int k0 = kbase + crow(i, hh), k1 = k0 + 32;
;                     float x0 = s0[i] * a.c2, x1 = s1[i] * a.c2;
;                     bool v0 = true, v1 = true;
;                     if (MODE == 1) { v0 = k0 <= qi; v1 = k1 <= qi; }
;                     if (MODE == 3) {
;                         const int st0 = qi - k0, st1 = qi - k1;
;                         v0 = (st0 >= 0) && (st0 <= 128) && (k0 >= 0); v1 = (st1 >= 0) && (st1 <= 128) && (k1 >= 0);
;                         x0 += biasL[min(max(st0, 0), 128)]; x1 += biasL[min(max(st1, 0), 128)];
;                     }
;                     x0 = v0 ? x0 : -1e30f; x1 = v1 ? x1 : -1e30f;
;                     s0[i] = x0; s1[i] = x1; mx = fmaxf(mx, fmaxf(x0, x1));
;                 }
;                 mx = fmaxf(mx, __shfl_xor(mx, 32));
;                 mnew = fmaxf(mrow, mx); alpha = ex2(mrow - mnew);
; #pragma unroll
;                 for (int i = 0; i < 16; ++i) {
;                     const float p0 = (s0[i] > -1e29f) ? ex2(s0[i] - mnew) : 0.f, p1 = (s1[i] > -1e29f) ? ex2(s1[i] - mnew) : 0.f;
;                     s0[i] = p0; s1[i] = p1; ls += p0 + p1;
;                 }
;             }
;             mrow = mnew;
;             lrow = lrow * alpha + ls;
.Lmla_fused:
	v_max3_f32 v0, v48, v49, v50
	v_max3_f32 v14, v80, v81, v82
	v_max3_f32 v0, v0, v51, v52
	v_max3_f32 v14, v14, v83, v84
	v_max3_f32 v0, v0, v53, v54
	v_max3_f32 v14, v14, v85, v86
	v_max3_f32 v0, v0, v55, v56
	v_max3_f32 v14, v14, v87, v88
	v_max3_f32 v0, v0, v57, v58
	v_max3_f32 v14, v14, v89, v90
	v_max3_f32 v0, v0, v59, v60
	v_max3_f32 v14, v14, v91, v92
	v_max3_f32 v0, v0, v61, v62
	v_max3_f32 v14, v14, v93, v94
	v_max3_f32 v0, v0, v63, v14
	v_max_f32_e32 v0, v0, v95
	s_lshl_b32 s7, s9, 1
	s_mov_b32 s6, 0x3e16c740
	v_mul_f32_e32 v0, 0x3e16c740, v0
	v_mov_b32_e32 v3, v0
	v_add_u32_e32 v158, s7, v200
	v_add_u32_e32 v159, s7, v201
	v_permlane32_swap_b32 v0, v3
	ds_read_b64_tr_b16 v[64:65], v158 offset:13568
	ds_read_b64_tr_b16 v[66:67], v158 offset:14592
	ds_read_b64_tr_b16 v[68:69], v159 offset:13568
	ds_read_b64_tr_b16 v[70:71], v159 offset:14592
	ds_read_b64_tr_b16 v[72:73], v158 offset:15616
	ds_read_b64_tr_b16 v[74:75], v158 offset:16640
	ds_read_b64_tr_b16 v[76:77], v159 offset:15616
	ds_read_b64_tr_b16 v[78:79], v159 offset:16640
	v_max3_f32 v231, v232, v0, v3
	v_sub_f32_e32 v2, v232, v231
	v_exp_f32_e32 v2, v2
	v_fma_f32 v48, v48, s6, -v231
	v_fma_f32 v49, v49, s6, -v231
	v_fma_f32 v50, v50, s6, -v231
	v_fma_f32 v51, v51, s6, -v231
	v_fma_f32 v52, v52, s6, -v231
	v_fma_f32 v53, v53, s6, -v231
	v_fma_f32 v54, v54, s6, -v231
	v_fma_f32 v55, v55, s6, -v231
	v_cmp_gt_f32_e32 vcc, 1.0, v2
	s_cbranch_vccz .Lmla_f_nors
	v_pk_mul_f32 v[46:47], v[46:47], v[2:3] op_sel_hi:[1,0]
	v_pk_mul_f32 v[44:45], v[44:45], v[2:3] op_sel_hi:[1,0]
	v_pk_mul_f32 v[42:43], v[42:43], v[2:3] op_sel_hi:[1,0]
	v_pk_mul_f32 v[40:41], v[40:41], v[2:3] op_sel_hi:[1,0]
	v_pk_mul_f32 v[38:39], v[38:39], v[2:3] op_sel_hi:[1,0]
	v_pk_mul_f32 v[36:37], v[36:37], v[2:3] op_sel_hi:[1,0]
	v_pk_mul_f32 v[34:35], v[34:35], v[2:3] op_sel_hi:[1,0]
	v_pk_mul_f32 v[32:33], v[32:33], v[2:3] op_sel_hi:[1,0]
	v_pk_mul_f32 v[30:31], v[30:31], v[2:3] op_sel_hi:[1,0]
	v_pk_mul_f32 v[28:29], v[28:29], v[2:3] op_sel_hi:[1,0]
	v_pk_mul_f32 v[26:27], v[26:27], v[2:3] op_sel_hi:[1,0]
	v_pk_mul_f32 v[24:25], v[24:25], v[2:3] op_sel_hi:[1,0]
	v_pk_mul_f32 v[22:23], v[22:23], v[2:3] op_sel_hi:[1,0]
	v_pk_mul_f32 v[20:21], v[20:21], v[2:3] op_sel_hi:[1,0]
	v_pk_mul_f32 v[18:19], v[18:19], v[2:3] op_sel_hi:[1,0]
	v_pk_mul_f32 v[16:17], v[16:17], v[2:3] op_sel_hi:[1,0]
